# normmod row reductions: DPP butterfly + readlane instead of six ds_bpermute hops
# speedup vs baseline: 1.0172x; 1.0051x over previous
; DI unsigned cvtpk(float lo, float hi) { f32x2_t v = {lo, hi}; bf16x2_t b = __builtin_convertvector(v, bf16x2_t); return __builtin_bit_cast(unsigned, b); }
; DI float shx(float v, int mask, int lane) { return __int_as_float(__builtin_amdgcn_ds_bpermute((lane ^ mask) << 2, __float_as_int(v))); }
; DI float wave_sum(float v, int lane) {
; #pragma unroll
;     for (int o = 1; o < 64; o <<= 1) v += shx(v, o, lane);
;     return v;
; }
; DI void phase_normmod(ArgsP a, int tb_, int l, int which, bool first, bool addp, bool ctx0, bool copyh, int MR, int vcu, int G) {
;     ...
;         const float r = rsqrtf(wave_sum(s, lane) * (1.f / D) + EPS);
;         u32x2* o = (u32x2*)(U + (size_t)m * D) + lane;
; #pragma unroll
;         for (int j = 0; j < 4; ++j) { const f32x4 y = v[j] * r * gv[j]; const f32x4 u = y * cv[j] + sv[j]; u32x2 w; w.x = cvtpk(u.x, u.y); w.y = cvtpk(u.z, u.w); o[64 * j] = w; }
.LBB0_19:
	s_or_b64 exec, exec, s[18:19]
	s_waitcnt vmcnt(1)
	v_pk_add_f32 v[74:75], v[74:75], 1.0 op_sel_hi:[1,0]
	v_pk_add_f32 v[72:73], v[72:73], 1.0 op_sel_hi:[1,0]
	v_pk_add_f32 v[62:63], v[62:63], 1.0 op_sel_hi:[1,0]
	v_pk_add_f32 v[60:61], v[60:61], 1.0 op_sel_hi:[1,0]
	v_pk_add_f32 v[58:59], v[58:59], 1.0 op_sel_hi:[1,0]
	v_pk_add_f32 v[56:57], v[56:57], 1.0 op_sel_hi:[1,0]
	s_waitcnt vmcnt(0)
	v_pk_add_f32 v[54:55], v[54:55], 1.0 op_sel_hi:[1,0]
	v_pk_add_f32 v[52:53], v[52:53], 1.0 op_sel_hi:[1,0]
	s_and_b64 s[4:5], exec, s[4:5]
	s_or_b64 s[16:17], s[4:5], s[16:17]
	v_add_f32_dpp v93, v93, v93 quad_perm:[1,0,3,2] row_mask:0xf bank_mask:0xf
	s_nop 1
	v_add_f32_dpp v93, v93, v93 quad_perm:[2,3,0,1] row_mask:0xf bank_mask:0xf
	s_nop 1
	v_add_f32_dpp v93, v93, v93 row_half_mirror row_mask:0xf bank_mask:0xf
	s_nop 1
	v_add_f32_dpp v93, v93, v93 row_mirror row_mask:0xf bank_mask:0xf
	s_nop 1
	v_add_f32_dpp v93, v93, v93 row_bcast:15 row_mask:0xa bank_mask:0xf
	s_nop 1
	v_add_f32_dpp v93, v93, v93 row_bcast:31 row_mask:0xc bank_mask:0xf
	s_nop 0
	v_readlane_b32 vcc_lo, v93, 63
	s_nop 1
	v_mov_b32_e32 v93, vcc_lo
	v_fmamk_f32 v93, v93, 0x3a800000, v230
	v_mul_f32_e32 v94, 0x4b800000, v93
	v_cmp_gt_f32_e32 vcc, s76, v93
	s_nop 1
	v_cndmask_b32_e32 v93, v93, v94, vcc
	v_rsq_f32_e32 v93, v93
	v_lshl_add_u64 v[94:95], v[86:87], 0, v[88:89]
	v_lshl_add_u64 v[88:89], v[88:89], 0, s[6:7]
	v_mul_f32_e32 v96, 0x45800000, v93
	v_cndmask_b32_e32 v96, v93, v96, vcc
	v_pk_mul_f32 v[70:71], v[70:71], v[96:97] op_sel_hi:[1,0]
	v_pk_mul_f32 v[68:69], v[68:69], v[96:97] op_sel_hi:[1,0]
	v_pk_mul_f32 v[78:79], v[78:79], v[96:97] op_sel_hi:[1,0]
	v_pk_mul_f32 v[76:77], v[76:77], v[96:97] op_sel_hi:[1,0]
	v_pk_mul_f32 v[66:67], v[66:67], v[96:97] op_sel_hi:[1,0]
	v_pk_mul_f32 v[64:65], v[64:65], v[96:97] op_sel_hi:[1,0]
	v_pk_mul_f32 v[32:33], v[32:33], v[68:69]
	v_pk_mul_f32 v[34:35], v[34:35], v[70:71]
	v_pk_mul_f32 v[28:29], v[28:29], v[76:77]
	v_pk_mul_f32 v[30:31], v[30:31], v[78:79]
	v_pk_mul_f32 v[44:45], v[44:45], v[64:65]
	v_pk_mul_f32 v[46:47], v[46:47], v[66:67]
	v_pk_fma_f32 v[34:35], v[74:75], v[34:35], v[42:43]
	v_pk_fma_f32 v[32:33], v[72:73], v[32:33], v[40:41]
	v_pk_fma_f32 v[26:27], v[62:63], v[30:31], v[26:27]
	v_pk_fma_f32 v[24:25], v[60:61], v[28:29], v[24:25]
	v_pk_fma_f32 v[38:39], v[58:59], v[46:47], v[38:39]
	v_pk_fma_f32 v[36:37], v[56:57], v[44:45], v[36:37]
	v_cvt_pk_bf16_f32 v32, v32, v33
	v_cvt_pk_bf16_f32 v33, v34, v35
	v_cvt_pk_bf16_f32 v24, v24, v25
	v_cvt_pk_bf16_f32 v25, v26, v27
	v_cvt_pk_bf16_f32 v34, v36, v37
	v_cvt_pk_bf16_f32 v35, v38, v39
	global_store_dwordx2 v[94:95], v[32:33], off offset:-1024
	global_store_dwordx2 v[94:95], v[34:35], off offset:-512
	global_store_dwordx2 v[94:95], v[24:25], off
	v_pk_mul_f32 v[24:25], v[50:51], v[96:97] op_sel_hi:[1,0]
	v_pk_mul_f32 v[26:27], v[48:49], v[96:97] op_sel_hi:[1,0]
	v_pk_mul_f32 v[22:23], v[22:23], v[24:25]
	v_pk_mul_f32 v[20:21], v[20:21], v[26:27]
	v_pk_fma_f32 v[18:19], v[54:55], v[22:23], v[18:19]
	v_pk_fma_f32 v[16:17], v[52:53], v[20:21], v[16:17]
	v_mov_b32_e32 v68, v0
	v_cvt_pk_bf16_f32 v16, v16, v17
	v_cvt_pk_bf16_f32 v17, v18, v19
	global_store_dwordx2 v[94:95], v[16:17], off offset:512
	v_mov_b32_e32 v94, v92
	v_mov_b32_e32 v69, v1
	v_mov_b32_e32 v70, v2
	v_mov_b32_e32 v71, v3
	v_mov_b32_e32 v64, v4
	v_mov_b32_e32 v65, v5
	v_mov_b32_e32 v66, v6
	v_mov_b32_e32 v67, v7
	v_mov_b32_e32 v76, v8
	v_mov_b32_e32 v77, v9
	v_mov_b32_e32 v78, v10
	v_mov_b32_e32 v79, v11
	v_mov_b32_e32 v48, v12
	v_mov_b32_e32 v49, v13
	v_mov_b32_e32 v50, v14
	v_mov_b32_e32 v51, v15
	s_andn2_b64 exec, exec, s[16:17]
	s_cbranch_execz .LBB0_28

; DI float bflo(unsigned u) { return __uint_as_float(u << 16); }
; DI float bfhi(unsigned u) { return __uint_as_float(u & 0xffff0000u); }
; DI void phase_normmod(ArgsP a, int tb_, int l, int which, bool first, bool addp, bool ctx0, bool copyh, int MR, int vcu, int G) {
;     ...
;         f32x4 v[4]; float s = 0.f; u32x4 raw[4];
; #pragma unroll
;         for (int j = 0; j < 4; ++j) raw[j] = nraw[j];
;         { const int mn = m + NGW; if (mn < MR) NM_LOAD(mn, nraw); }
;         const f32x4* gp = (const f32x4*)g + lane; const f32x4* sh = (const f32x4*)(mod + (size_t)br * (NMOD * D) + (3 * which) * D) + lane; const f32x4* scp = (const f32x4*)(mod + (size_t)br * (NMOD * D) + (3 * which + 1) * D) + lane;
;         f32x4 gv[4], sv[4], cv[4];
; #pragma unroll
;         for (int j = 0; j < 4; ++j) { gv[j] = gp[64 * j]; sv[j] = sh[64 * j]; cv[j] = scp[64 * j] + 1.f; }
; #pragma unroll
;         for (int j = 0; j < 4; ++j) { v[j] = isb ? (f32x4){bflo(raw[j].x), bfhi(raw[j].x), bflo(raw[j].y), bfhi(raw[j].y)} : __builtin_bit_cast(f32x4, raw[j]);
;             s += (v[j].x * v[j].x + v[j].y * v[j].y) + (v[j].z * v[j].z + v[j].w * v[j].w); }
;         if (copyh && isb) { u32x2* c = (u32x2*)(hcopy + (size_t)m * D) + lane;
; #pragma unroll
;             for (int j = 0; j < 4; ++j) c[64 * j] = (u32x2){raw[j].x, raw[j].y}; }
;         if (addp && m >= ML) { const f32x4* pp = (const f32x4*)((const float*)(a->ws + A_PART) + (size_t)(m - ML) * D) + lane; s = 0.f;
; #pragma unroll
;             for (int jh = 0; jh < 2; ++jh) { f32x4 pv[2][8];
; #pragma unroll
;                 for (int jj = 0; jj < 2; ++jj)
; #pragma unroll
;                     for (int p = 0; p < 8; ++p) pv[jj][p] = pp[(size_t)p * MC * (D / 4) + 64 * (2 * jh + jj)];
;                 __builtin_amdgcn_sched_barrier(0);
; #pragma unroll
;                 for (int jj = 0; jj < 2; ++jj) { const int j = 2 * jh + jj;
; #pragma unroll
;                     for (int p = 0; p < 8; ++p) v[j] = v[j] + pv[jj][p];
;                     s += (v[j].x * v[j].x + v[j].y * v[j].y) + (v[j].z * v[j].z + v[j].w * v[j].w); } }
;             float* hrow = hc + (size_t)(m - ML) * D;
; #pragma unroll
;             for (int j = 0; j < 4; ++j) ((f32x4*)hrow + lane)[64 * j] = v[j]; }
;         const float r = rsqrtf(wave_sum(s, lane) * (1.f / D) + EPS);
;         u32x2* o = (u32x2*)(U + (size_t)m * D) + lane;
; #pragma unroll
.LBB0_222:
	s_or_b64 exec, exec, s[18:19]
	v_pk_mul_f32 v[86:87], v[14:15], v[14:15]
	v_pk_mul_f32 v[88:89], v[12:13], v[12:13]
	v_min_i32_e32 v46, 0x8000, v33
	v_pk_mov_b32 v[92:93], v[88:89], v[86:87] op_sel:[1,0]
	v_mov_b32_e32 v89, v87
	v_pk_add_f32 v[86:87], v[92:93], v[88:89]
	v_pk_mul_f32 v[88:89], v[10:11], v[10:11]
	v_pk_mul_f32 v[92:93], v[8:9], v[8:9]
	v_ashrrev_i32_e32 v46, 12, v46
	v_pk_mov_b32 v[94:95], v[92:93], v[88:89] op_sel:[1,0]
	v_mov_b32_e32 v93, v89
	v_pk_add_f32 v[88:89], v[94:95], v[92:93]
	v_mul_f32_e32 v92, v0, v0
	v_mul_f32_e32 v93, v1, v1
	v_pk_add_f32 v[86:87], v[86:87], v[86:87] op_sel:[0,1] op_sel_hi:[1,0]
	v_pk_add_f32 v[88:89], v[88:89], v[88:89] op_sel:[0,1] op_sel_hi:[1,0]
	v_mul_hi_i32_i24_e32 v47, 0x9000, v46
	v_mul_i32_i24_e32 v46, 0x9000, v46
	v_mov_b32_e32 v87, v92
	v_mov_b32_e32 v89, v93
	v_lshl_add_u64 v[46:47], s[12:13], 0, v[46:47]
	v_pk_add_f32 v[86:87], v[86:87], v[88:89]
	v_mul_f32_e32 v88, v5, v5
	v_mul_f32_e32 v92, v7, v7
	v_lshl_add_u64 v[90:91], v[46:47], 0, v[188:189]
	v_mul_f32_e32 v94, v2, v2
	v_mul_f32_e32 v95, v3, v3
	v_pk_fma_f32 v[88:89], v[4:5], v[4:5], v[88:89] op_sel_hi:[1,1,0]
	v_pk_fma_f32 v[92:93], v[6:7], v[6:7], v[92:93] op_sel_hi:[1,1,0]
	s_mov_b64 s[4:5], 0x1000
	v_add_co_u32_e32 v78, vcc, s93, v90
	v_mov_b32_e32 v89, v94
	v_mov_b32_e32 v93, v95
	v_lshl_add_u64 v[82:83], v[90:91], 0, s[4:5]
	v_addc_co_u32_e32 v79, vcc, 0, v91, vcc
	v_pk_add_f32 v[88:89], v[88:89], v[92:93]
	global_load_dwordx4 v[46:49], v[34:35], off
	global_load_dwordx4 v[50:53], v[34:35], off offset:1024
	global_load_dwordx4 v[54:57], v[90:91], off
	global_load_dwordx4 v[58:61], v[90:91], off offset:1024
	global_load_dwordx4 v[62:65], v[34:35], off offset:2048
	global_load_dwordx4 v[66:69], v[90:91], off offset:2048
	global_load_dwordx4 v[70:73], v[82:83], off offset:1024
	global_load_dwordx4 v[74:77], v[82:83], off offset:2048
	s_nop 0
	global_load_dwordx4 v[78:81], v[78:79], off
	s_nop 0
	global_load_dwordx4 v[82:85], v[82:83], off offset:3072
	v_pk_add_f32 v[86:87], v[86:87], v[88:89]
	v_add_u32_e32 v33, s10, v33
	v_add_f32_e32 v94, v86, v87
	global_load_dwordx4 v[86:89], v[34:35], off offset:3072
	s_nop 0
	global_load_dwordx4 v[90:93], v[90:91], off offset:3072
	v_lshl_add_u64 v[38:39], v[38:39], 0, s[10:11]
	v_add_f32_dpp v94, v94, v94 quad_perm:[1,0,3,2] row_mask:0xf bank_mask:0xf
	s_nop 1
	v_add_f32_dpp v94, v94, v94 quad_perm:[2,3,0,1] row_mask:0xf bank_mask:0xf
	s_nop 1
	v_add_f32_dpp v94, v94, v94 row_half_mirror row_mask:0xf bank_mask:0xf
	s_nop 1
	v_add_f32_dpp v94, v94, v94 row_mirror row_mask:0xf bank_mask:0xf
	s_nop 1
	v_add_f32_dpp v94, v94, v94 row_bcast:15 row_mask:0xa bank_mask:0xf
	s_nop 1
	v_add_f32_dpp v94, v94, v94 row_bcast:31 row_mask:0xc bank_mask:0xf
	s_nop 0
	v_readlane_b32 vcc_lo, v94, 63
	s_nop 1
	v_mov_b32_e32 v94, vcc_lo
	v_fmamk_f32 v94, v94, 0x3a800000, v230
	v_mul_f32_e32 v95, 0x4b800000, v94
	v_cmp_gt_f32_e32 vcc, s76, v94
	s_waitcnt vmcnt(5)
	v_pk_add_f32 v[72:73], v[72:73], 1.0 op_sel_hi:[1,0]
	v_cndmask_b32_e32 v94, v94, v95, vcc
	v_rsq_f32_e32 v94, v94
	v_pk_add_f32 v[70:71], v[70:71], 1.0 op_sel_hi:[1,0]
	s_waitcnt vmcnt(4)
	v_pk_add_f32 v[76:77], v[76:77], 1.0 op_sel_hi:[1,0]
	v_pk_add_f32 v[74:75], v[74:75], 1.0 op_sel_hi:[1,0]
	v_mul_f32_e32 v95, 0x45800000, v94
	v_cndmask_b32_e32 v94, v94, v95, vcc
	v_pk_mul_f32 v[14:15], v[14:15], v[94:95] op_sel_hi:[1,0]
	v_pk_mul_f32 v[12:13], v[12:13], v[94:95] op_sel_hi:[1,0]
	v_pk_mul_f32 v[10:11], v[10:11], v[94:95] op_sel_hi:[1,0]
	v_pk_mul_f32 v[8:9], v[8:9], v[94:95] op_sel_hi:[1,0]
	v_pk_mul_f32 v[6:7], v[6:7], v[94:95] op_sel_hi:[1,0]
	v_pk_mul_f32 v[4:5], v[4:5], v[94:95] op_sel_hi:[1,0]
	v_pk_mul_f32 v[2:3], v[2:3], v[94:95] op_sel_hi:[1,0]
	v_pk_mul_f32 v[0:1], v[0:1], v[94:95] op_sel_hi:[1,0]
	v_pk_mul_f32 v[12:13], v[46:47], v[12:13]
	v_pk_mul_f32 v[14:15], v[48:49], v[14:15]
	s_waitcnt vmcnt(3)
	v_pk_add_f32 v[46:47], v[80:81], 1.0 op_sel_hi:[1,0]
	v_pk_add_f32 v[48:49], v[78:79], 1.0 op_sel_hi:[1,0]
	s_waitcnt vmcnt(2)
	v_pk_add_f32 v[78:79], v[84:85], 1.0 op_sel_hi:[1,0]
	v_pk_add_f32 v[80:81], v[82:83], 1.0 op_sel_hi:[1,0]
	v_pk_mul_f32 v[8:9], v[50:51], v[8:9]
	v_pk_mul_f32 v[10:11], v[52:53], v[10:11]
	v_pk_mul_f32 v[4:5], v[62:63], v[4:5]
	v_pk_mul_f32 v[6:7], v[64:65], v[6:7]
	s_waitcnt vmcnt(1)
	v_pk_mul_f32 v[0:1], v[86:87], v[0:1]
	v_pk_mul_f32 v[2:3], v[88:89], v[2:3]
	v_pk_fma_f32 v[14:15], v[46:47], v[14:15], v[56:57]
	v_pk_fma_f32 v[12:13], v[48:49], v[12:13], v[54:55]
	v_pk_fma_f32 v[10:11], v[72:73], v[10:11], v[60:61]
	v_pk_fma_f32 v[8:9], v[70:71], v[8:9], v[58:59]
	v_pk_fma_f32 v[6:7], v[76:77], v[6:7], v[68:69]
	v_pk_fma_f32 v[4:5], v[74:75], v[4:5], v[66:67]
	s_waitcnt vmcnt(0)
	v_pk_fma_f32 v[2:3], v[78:79], v[2:3], v[92:93]
	v_pk_fma_f32 v[0:1], v[80:81], v[0:1], v[90:91]
	v_cvt_pk_bf16_f32 v12, v12, v13
	v_cvt_pk_bf16_f32 v13, v14, v15
	v_cvt_pk_bf16_f32 v8, v8, v9
	v_cvt_pk_bf16_f32 v9, v10, v11
	v_cvt_pk_bf16_f32 v4, v4, v5
	v_cvt_pk_bf16_f32 v5, v6, v7
	v_cvt_pk_bf16_f32 v0, v0, v1
	v_cvt_pk_bf16_f32 v1, v2, v3
	global_store_dwordx2 v[36:37], v[12:13], off offset:-1024
	global_store_dwordx2 v[36:37], v[8:9], off offset:-512
	global_store_dwordx2 v[36:37], v[4:5], off
	global_store_dwordx2 v[36:37], v[0:1], off offset:512
	v_cmp_lt_i32_e32 vcc, s70, v33
	v_mov_b64_e32 v[12:13], v[16:17]
	v_mov_b64_e32 v[8:9], v[20:21]
	v_mov_b64_e32 v[4:5], v[24:25]
	v_mov_b64_e32 v[0:1], v[28:29]
	v_lshl_add_u64 v[36:37], v[36:37], 0, s[14:15]
	s_or_b64 s[16:17], vcc, s[16:17]
	v_mov_b64_e32 v[14:15], v[18:19]
	v_mov_b64_e32 v[10:11], v[22:23]
	v_mov_b64_e32 v[6:7], v[26:27]
	v_mov_b64_e32 v[2:3], v[30:31]
	s_andn2_b64 exec, exec, s[16:17]
	s_cbranch_execz .LBB0_225

; DI unsigned cvtpk(float lo, float hi) { f32x2_t v = {lo, hi}; bf16x2_t b = __builtin_convertvector(v, bf16x2_t); return __builtin_bit_cast(unsigned, b); }
; DI void phase_normmod(ArgsP a, int tb_, int l, int which, bool first, bool addp, bool ctx0, bool copyh, int MR, int vcu, int G) {
;     ...
;         const float r = rsqrtf(wave_sum(s, lane) * (1.f / D) + EPS);
;         u32x2* o = (u32x2*)(U + (size_t)m * D) + lane;
; #pragma unroll
;         for (int j = 0; j < 4; ++j) { const f32x4 y = v[j] * r * gv[j]; const f32x4 u = y * cv[j] + sv[j]; u32x2 w; w.x = cvtpk(u.x, u.y); w.y = cvtpk(u.z, u.w); o[64 * j] = w; }
.LBB0_731:
	s_or_b64 exec, exec, s[22:23]
	s_waitcnt vmcnt(1)
	v_pk_add_f32 v[74:75], v[74:75], 1.0 op_sel_hi:[1,0]
	v_pk_add_f32 v[72:73], v[72:73], 1.0 op_sel_hi:[1,0]
	v_pk_add_f32 v[62:63], v[62:63], 1.0 op_sel_hi:[1,0]
	v_pk_add_f32 v[60:61], v[60:61], 1.0 op_sel_hi:[1,0]
	v_pk_add_f32 v[58:59], v[58:59], 1.0 op_sel_hi:[1,0]
	v_pk_add_f32 v[56:57], v[56:57], 1.0 op_sel_hi:[1,0]
	s_waitcnt vmcnt(0)
	v_pk_add_f32 v[54:55], v[54:55], 1.0 op_sel_hi:[1,0]
	v_pk_add_f32 v[52:53], v[52:53], 1.0 op_sel_hi:[1,0]
	s_and_b64 s[4:5], exec, s[6:7]
	s_or_b64 s[8:9], s[4:5], s[8:9]
	v_add_f32_dpp v94, v95, v95 quad_perm:[1,0,3,2] row_mask:0xf bank_mask:0xf
	s_nop 1
	v_add_f32_dpp v94, v94, v94 quad_perm:[2,3,0,1] row_mask:0xf bank_mask:0xf
	s_nop 1
	v_add_f32_dpp v94, v94, v94 row_half_mirror row_mask:0xf bank_mask:0xf
	s_nop 1
	v_add_f32_dpp v94, v94, v94 row_mirror row_mask:0xf bank_mask:0xf
	s_nop 1
	v_add_f32_dpp v94, v94, v94 row_bcast:15 row_mask:0xa bank_mask:0xf
	s_nop 1
	v_add_f32_dpp v94, v94, v94 row_bcast:31 row_mask:0xc bank_mask:0xf
	s_nop 0
	v_readlane_b32 vcc_lo, v94, 63
	s_nop 1
	v_mov_b32_e32 v94, vcc_lo
	v_fmamk_f32 v94, v94, 0x3a800000, v230
	v_mul_f32_e32 v95, 0x4b800000, v94
	v_cmp_gt_f32_e32 vcc, s76, v94
	s_nop 1
	v_cndmask_b32_e32 v94, v94, v95, vcc
	v_rsq_f32_e32 v96, v94
	v_lshl_add_u64 v[94:95], v[88:89], 0, v[90:91]
	v_lshl_add_u64 v[90:91], v[90:91], 0, s[10:11]
	v_mul_f32_e32 v97, 0x45800000, v96
	v_cndmask_b32_e32 v96, v96, v97, vcc
	v_pk_mul_f32 v[70:71], v[70:71], v[96:97] op_sel_hi:[1,0]
	v_pk_mul_f32 v[68:69], v[68:69], v[96:97] op_sel_hi:[1,0]
	v_pk_mul_f32 v[78:79], v[78:79], v[96:97] op_sel_hi:[1,0]
	v_pk_mul_f32 v[76:77], v[76:77], v[96:97] op_sel_hi:[1,0]
	v_pk_mul_f32 v[66:67], v[66:67], v[96:97] op_sel_hi:[1,0]
	v_pk_mul_f32 v[64:65], v[64:65], v[96:97] op_sel_hi:[1,0]
	v_pk_mul_f32 v[32:33], v[32:33], v[68:69]
	v_pk_mul_f32 v[34:35], v[34:35], v[70:71]
	v_pk_mul_f32 v[28:29], v[28:29], v[76:77]
	v_pk_mul_f32 v[30:31], v[30:31], v[78:79]
	v_pk_mul_f32 v[44:45], v[44:45], v[64:65]
	v_pk_mul_f32 v[46:47], v[46:47], v[66:67]
	v_pk_fma_f32 v[34:35], v[74:75], v[34:35], v[42:43]
	v_pk_fma_f32 v[32:33], v[72:73], v[32:33], v[40:41]
	v_pk_fma_f32 v[26:27], v[62:63], v[30:31], v[26:27]
	v_pk_fma_f32 v[24:25], v[60:61], v[28:29], v[24:25]
	v_pk_fma_f32 v[38:39], v[58:59], v[46:47], v[38:39]
	v_pk_fma_f32 v[36:37], v[56:57], v[44:45], v[36:37]
	v_cvt_pk_bf16_f32 v32, v32, v33
	v_cvt_pk_bf16_f32 v33, v34, v35
	v_cvt_pk_bf16_f32 v24, v24, v25
	v_cvt_pk_bf16_f32 v25, v26, v27
	v_cvt_pk_bf16_f32 v34, v36, v37
	v_cvt_pk_bf16_f32 v35, v38, v39
	global_store_dwordx2 v[94:95], v[32:33], off offset:-1024
	global_store_dwordx2 v[94:95], v[34:35], off offset:-512
	global_store_dwordx2 v[94:95], v[24:25], off
	v_pk_mul_f32 v[24:25], v[50:51], v[96:97] op_sel_hi:[1,0]
	v_pk_mul_f32 v[26:27], v[48:49], v[96:97] op_sel_hi:[1,0]
	v_pk_mul_f32 v[22:23], v[22:23], v[24:25]
	v_pk_mul_f32 v[20:21], v[20:21], v[26:27]
	v_pk_fma_f32 v[18:19], v[54:55], v[22:23], v[18:19]
	v_pk_fma_f32 v[16:17], v[52:53], v[20:21], v[16:17]
	v_mov_b32_e32 v68, v0
	v_cvt_pk_bf16_f32 v16, v16, v17
	v_cvt_pk_bf16_f32 v17, v18, v19
	global_store_dwordx2 v[94:95], v[16:17], off offset:512
	v_mov_b32_e32 v94, v188
	v_mov_b32_e32 v69, v1
	v_mov_b32_e32 v70, v2
	v_mov_b32_e32 v71, v3
	v_mov_b32_e32 v64, v4
	v_mov_b32_e32 v65, v5
	v_mov_b32_e32 v66, v6
	v_mov_b32_e32 v67, v7
	v_mov_b32_e32 v76, v8
	v_mov_b32_e32 v77, v9
	v_mov_b32_e32 v78, v10
	v_mov_b32_e32 v79, v11
	v_mov_b32_e32 v48, v12
	v_mov_b32_e32 v49, v13
	v_mov_b32_e32 v50, v14
	v_mov_b32_e32 v51, v15
	s_andn2_b64 exec, exec, s[8:9]
	s_cbranch_execz .LBB0_742

; DI unsigned cvtpk(float lo, float hi) { f32x2_t v = {lo, hi}; bf16x2_t b = __builtin_convertvector(v, bf16x2_t); return __builtin_bit_cast(unsigned, b); }
; DI void phase_normmod(ArgsP a, int tb_, int l, int which, bool first, bool addp, bool ctx0, bool copyh, int MR, int vcu, int G) {
;     ...
;         const float r = rsqrtf(wave_sum(s, lane) * (1.f / D) + EPS);
;         u32x2* o = (u32x2*)(U + (size_t)m * D) + lane;
; #pragma unroll
;         for (int j = 0; j < 4; ++j) { const f32x4 y = v[j] * r * gv[j]; const f32x4 u = y * cv[j] + sv[j]; u32x2 w; w.x = cvtpk(u.x, u.y); w.y = cvtpk(u.z, u.w); o[64 * j] = w; }
.LBB0_1914:
	s_or_b64 exec, exec, s[8:9]
	s_waitcnt vmcnt(1)
	v_pk_add_f32 v[98:99], v[76:77], 1.0 op_sel_hi:[1,0]
	v_pk_add_f32 v[76:77], v[66:67], 1.0 op_sel_hi:[1,0]
	s_waitcnt vmcnt(0)
	v_pk_add_f32 v[66:67], v[72:73], 1.0 op_sel_hi:[1,0]
	v_pk_add_f32 v[82:83], v[78:79], 1.0 op_sel_hi:[1,0]
	v_pk_add_f32 v[78:79], v[64:65], 1.0 op_sel_hi:[1,0]
	s_mov_b32 s2, 0xa00000
	v_pk_add_f32 v[70:71], v[70:71], 1.0 op_sel_hi:[1,0]
	v_pk_add_f32 v[68:69], v[68:69], 1.0 op_sel_hi:[1,0]
	v_pk_add_f32 v[64:65], v[74:75], 1.0 op_sel_hi:[1,0]
	s_and_b64 s[4:5], exec, s[6:7]
	s_or_b64 s[18:19], s[4:5], s[18:19]
	v_lshl_add_u64 v[92:93], v[92:93], 0, s[10:11]
	v_lshl_add_u64 v[94:95], v[94:95], 0, s[10:11]
	v_mov_b32_e32 v80, v126
	v_add_f32_dpp v72, v81, v81 quad_perm:[1,0,3,2] row_mask:0xf bank_mask:0xf
	s_nop 1
	v_add_f32_dpp v72, v72, v72 quad_perm:[2,3,0,1] row_mask:0xf bank_mask:0xf
	s_nop 1
	v_add_f32_dpp v72, v72, v72 row_half_mirror row_mask:0xf bank_mask:0xf
	s_nop 1
	v_add_f32_dpp v72, v72, v72 row_mirror row_mask:0xf bank_mask:0xf
	s_nop 1
	v_add_f32_dpp v72, v72, v72 row_bcast:15 row_mask:0xa bank_mask:0xf
	s_nop 1
	v_add_f32_dpp v72, v72, v72 row_bcast:31 row_mask:0xc bank_mask:0xf
	s_nop 0
	v_readlane_b32 vcc_lo, v72, 63
	s_nop 1
	v_mov_b32_e32 v72, vcc_lo
	v_fmamk_f32 v72, v72, 0x3a800000, v230
	v_cmp_gt_f32_e32 vcc, s76, v72
	v_mul_f32_e32 v73, 0x4b800000, v72
	s_nop 0
	v_cndmask_b32_e32 v72, v72, v73, vcc
	v_rsq_f32_e32 v72, v72
	s_nop 0
	v_mul_f32_e32 v73, 0x45800000, v72
	v_cndmask_b32_e32 v72, v72, v73, vcc
	v_pk_mul_f32 v[62:63], v[62:63], v[72:73] op_sel_hi:[1,0]
	v_pk_mul_f32 v[60:61], v[60:61], v[72:73] op_sel_hi:[1,0]
	v_pk_mul_f32 v[54:55], v[54:55], v[62:63]
	v_pk_mul_f32 v[52:53], v[52:53], v[60:61]
	v_pk_mul_f32 v[50:51], v[50:51], v[72:73] op_sel_hi:[1,0]
	v_pk_mul_f32 v[48:49], v[48:49], v[72:73] op_sel_hi:[1,0]
	v_pk_fma_f32 v[54:55], v[82:83], v[54:55], v[58:59]
	v_pk_fma_f32 v[52:53], v[98:99], v[52:53], v[56:57]
	v_pk_mul_f32 v[36:37], v[36:37], v[48:49]
	v_pk_mul_f32 v[38:39], v[38:39], v[50:51]
	v_cvt_pk_bf16_f32 v52, v52, v53
	v_cvt_pk_bf16_f32 v53, v54, v55
	v_add_co_u32_e32 v54, vcc, s2, v96
	v_pk_fma_f32 v[34:35], v[76:77], v[38:39], v[34:35]
	v_pk_fma_f32 v[32:33], v[78:79], v[36:37], v[32:33]
	v_addc_co_u32_e32 v55, vcc, 0, v97, vcc
	v_cvt_pk_bf16_f32 v32, v32, v33
	v_cvt_pk_bf16_f32 v33, v34, v35
	global_store_dwordx2 v[54:55], v[32:33], off offset:512
	v_pk_mul_f32 v[32:33], v[46:47], v[72:73] op_sel_hi:[1,0]
	v_pk_mul_f32 v[34:35], v[44:45], v[72:73] op_sel_hi:[1,0]
	v_pk_mul_f32 v[30:31], v[30:31], v[32:33]
	v_pk_mul_f32 v[28:29], v[28:29], v[34:35]
	v_pk_fma_f32 v[26:27], v[70:71], v[30:31], v[26:27]
	v_pk_fma_f32 v[24:25], v[68:69], v[28:29], v[24:25]
	v_mov_b32_e32 v60, v0
	v_cvt_pk_bf16_f32 v24, v24, v25
	v_cvt_pk_bf16_f32 v25, v26, v27
	global_store_dwordx2 v[54:55], v[24:25], off offset:1024
	v_pk_mul_f32 v[24:25], v[42:43], v[72:73] op_sel_hi:[1,0]
	v_pk_mul_f32 v[26:27], v[40:41], v[72:73] op_sel_hi:[1,0]
	v_pk_mul_f32 v[22:23], v[22:23], v[24:25]
	v_pk_mul_f32 v[20:21], v[20:21], v[26:27]
	v_pk_fma_f32 v[18:19], v[64:65], v[22:23], v[18:19]
	v_pk_fma_f32 v[16:17], v[66:67], v[20:21], v[16:17]
	v_mov_b32_e32 v61, v1
	v_cvt_pk_bf16_f32 v16, v16, v17
	v_cvt_pk_bf16_f32 v17, v18, v19
	v_mov_b32_e32 v62, v2
	v_mov_b32_e32 v63, v3
	v_mov_b32_e32 v48, v4
	v_mov_b32_e32 v49, v5
	v_mov_b32_e32 v50, v6
	v_mov_b32_e32 v51, v7
	v_mov_b32_e32 v44, v8
	v_mov_b32_e32 v45, v9
	v_mov_b32_e32 v46, v10
	v_mov_b32_e32 v47, v11
	v_mov_b32_e32 v40, v12
	v_mov_b32_e32 v41, v13
	v_mov_b32_e32 v42, v14
	v_mov_b32_e32 v43, v15
	global_store_dwordx2 v[54:55], v[52:53], off
	global_store_dwordx2 v[54:55], v[16:17], off offset:1536
	s_andn2_b64 exec, exec, s[18:19]
	s_cbranch_execz .LBB0_1925
